# adds: streamed fragment loads in the K loops of the P3 gated-merge sample tile and the P4 sample tile (were one load per vmcnt(0) round trip)
# baseline (speedup 1.0000x reference)
.LBB0_608:
	s_lshl_b32 s11, s10, 2
	s_andn2_b32 s11, s11, 63
	s_addk_i32 s11, 0x4000
	v_add_u32_e32 v0, s11, v114
	s_lshl_b32 s12, s10, 6
	v_ashrrev_i32_e32 v1, 31, v0
	s_and_b32 s12, s12, 0x3c0
	v_lshlrev_b64 v[0:1], 10, v[0:1]
	v_or_b32_e32 v0, s12, v0
	v_or_b32_e32 v0, v0, v72
	v_readlane_b32 s12, v254, 2
	v_lshlrev_b64 v[0:1], 1, v[0:1]
	v_readlane_b32 s13, v254, 3
	v_lshl_add_u64 v[80:81], s[78:79], 0, v[0:1]
	s_andn2_b64 vcc, exec, s[4:5]
	v_lshl_add_u64 v[0:1], s[12:13], 0, v[0:1]
	global_load_dwordx4 v[4:7], v[80:81], off
	s_nop 0
	global_load_dwordx4 v[0:3], v[0:1], off
	s_cbranch_vccnz .LBB0_606
	s_and_b32 s11, s7, 0x3c0
	v_or_b32_e32 v14, s11, v73
	v_lshlrev_b32_e32 v15, 1, v14
	v_or_b32_e32 v8, 32, v15
	v_mad_i64_i32 v[82:83], s[12:13], s0, v8, v[76:77]
	v_or_b32_e32 v8, 0x60, v15
	s_and_b32 s11, s6, 0xffffffc0
	v_mad_i64_i32 v[84:85], s[12:13], s0, v8, v[76:77]
	v_add_u32_e32 v8, s11, v125
	v_ashrrev_i32_e32 v9, 31, v8
	v_lshlrev_b64 v[10:11], 1, v[8:9]
	v_lshl_add_u64 v[12:13], v[10:11], 0, 64
	v_mul_lo_u32 v13, s0, v13
	v_mul_lo_u32 v16, s1, v12
	v_mad_u64_u32 v[86:87], s[12:13], s0, v12, v[78:79]
	v_add3_u32 v87, v16, v87, v13
	v_lshl_add_u64 v[12:13], v[10:11], 0, s[42:43]
	v_mul_lo_u32 v13, s0, v13
	v_mul_lo_u32 v16, s1, v12
	v_mad_u64_u32 v[88:89], s[12:13], s0, v12, v[78:79]
	v_or_b32_e32 v12, 64, v15
	v_lshl_add_u64 v[10:11], v[10:11], 0, 32
	v_add3_u32 v89, v16, v89, v13
	v_mad_i64_i32 v[90:91], s[12:13], s0, v12, v[76:77]
	v_mad_u64_u32 v[92:93], s[12:13], s8, v14, v[76:77]
	v_mul_lo_u32 v11, s0, v11
	v_mul_lo_u32 v12, s1, v10
	v_mad_u64_u32 v[94:95], s[12:13], s0, v10, v[78:79]
	v_mul_lo_u32 v9, s8, v9
	v_mul_lo_u32 v10, s9, v8
	v_mad_u64_u32 v[96:97], s[12:13], s8, v8, v[78:79]
	v_mov_b32_e32 v16, 0
	v_mad_i32_i24 v93, s9, v14, v93
	v_add3_u32 v95, v12, v95, v11
	v_add3_u32 v97, v10, v97, v9
	s_mov_b32 s11, 0
	v_mov_b32_e32 v17, v16
	v_mov_b32_e32 v18, v16
	v_mov_b32_e32 v19, v16
	v_mov_b32_e32 v40, v16
	v_mov_b32_e32 v41, v16
	v_mov_b32_e32 v42, v16
	v_mov_b32_e32 v43, v16
	v_mov_b32_e32 v44, v16
	v_mov_b32_e32 v45, v16
	v_mov_b32_e32 v46, v16
	v_mov_b32_e32 v47, v16
	v_mov_b32_e32 v48, v16
	v_mov_b32_e32 v49, v16
	v_mov_b32_e32 v50, v16
	v_mov_b32_e32 v51, v16
	v_mov_b32_e32 v52, v16
	v_mov_b32_e32 v53, v16
	v_mov_b32_e32 v54, v16
	v_mov_b32_e32 v55, v16
	v_mov_b32_e32 v32, v16
	v_mov_b32_e32 v33, v16
	v_mov_b32_e32 v34, v16
	v_mov_b32_e32 v35, v16
	v_mov_b32_e32 v24, v16
	v_mov_b32_e32 v25, v16
	v_mov_b32_e32 v26, v16
	v_mov_b32_e32 v27, v16
	v_mov_b32_e32 v12, v16
	v_mov_b32_e32 v13, v16
	v_mov_b32_e32 v14, v16
	v_mov_b32_e32 v15, v16
	v_mov_b32_e32 v36, v16
	v_mov_b32_e32 v37, v16
	v_mov_b32_e32 v38, v16
	v_mov_b32_e32 v39, v16
	v_mov_b32_e32 v28, v16
	v_mov_b32_e32 v29, v16
	v_mov_b32_e32 v30, v16
	v_mov_b32_e32 v31, v16
	v_mov_b32_e32 v20, v16
	v_mov_b32_e32 v21, v16
	v_mov_b32_e32 v22, v16
	v_mov_b32_e32 v23, v16
	v_mov_b32_e32 v8, v16
	v_mov_b32_e32 v9, v16
	v_mov_b32_e32 v10, v16
	v_mov_b32_e32 v11, v16
	v_mov_b32_e32 v64, v16
	v_mov_b32_e32 v65, v16
	v_mov_b32_e32 v66, v16
	v_mov_b32_e32 v67, v16
	v_mov_b32_e32 v60, v16
	v_mov_b32_e32 v61, v16
	v_mov_b32_e32 v62, v16
	v_mov_b32_e32 v63, v16
	v_mov_b32_e32 v68, v16
	v_mov_b32_e32 v69, v16
	v_mov_b32_e32 v70, v16
	v_mov_b32_e32 v71, v16
	v_mov_b32_e32 v56, v16
	v_mov_b32_e32 v57, v16
	v_mov_b32_e32 v58, v16
	v_mov_b32_e32 v59, v16
	s_cmpk_lg_i32 s3, 0x100
	s_cbranch_scc1 .LBB0_610
	v_lshl_add_u64 v[112:113], v[92:93], 0, v[74:75]
	v_lshl_add_u64 v[110:111], v[82:83], 0, v[74:75]
	v_lshl_add_u64 v[106:107], v[90:91], 0, v[74:75]
	v_lshl_add_u64 v[104:105], v[84:85], 0, v[74:75]
	v_lshl_add_u64 v[108:109], v[96:97], 0, v[74:75]
	v_lshl_add_u64 v[100:101], v[94:95], 0, v[74:75]
	v_lshl_add_u64 v[102:103], v[86:87], 0, v[74:75]
	v_lshl_add_u64 v[98:99], v[88:89], 0, v[74:75]
	global_load_dwordx4 v[130:133], v[112:113], off
	global_load_dwordx4 v[134:137], v[110:111], off
	global_load_dwordx4 v[138:141], v[106:107], off
	global_load_dwordx4 v[142:145], v[104:105], off
	global_load_dwordx4 v[146:149], v[108:109], off
	global_load_dwordx4 v[150:153], v[100:101], off
	global_load_dwordx4 v[154:157], v[102:103], off
	global_load_dwordx4 v[158:161], v[98:99], off
	global_load_dwordx4 v[162:165], v[112:113], off offset:16
	global_load_dwordx4 v[166:169], v[110:111], off offset:16
	global_load_dwordx4 v[170:173], v[106:107], off offset:16
	global_load_dwordx4 v[174:177], v[104:105], off offset:16
	global_load_dwordx4 v[178:181], v[108:109], off offset:16
	global_load_dwordx4 v[182:185], v[100:101], off offset:16
	global_load_dwordx4 v[186:189], v[102:103], off offset:16
	global_load_dwordx4 v[198:201], v[98:99], off offset:16
	global_load_dwordx4 v[218:221], v[112:113], off offset:128
	global_load_dwordx4 v[222:225], v[110:111], off offset:128
	global_load_dwordx4 v[226:229], v[106:107], off offset:128
	global_load_dwordx4 v[230:233], v[104:105], off offset:128
	global_load_dwordx4 v[234:237], v[108:109], off offset:128
	global_load_dwordx4 v[238:241], v[100:101], off offset:128
	global_load_dwordx4 v[246:249], v[102:103], off offset:128
	s_waitcnt vmcnt(18)
	v_mfma_f32_16x16x32_bf16 v[16:19], v[130:133], v[146:149], v[16:19]
	s_waitcnt vmcnt(18)
	v_mfma_f32_16x16x32_bf16 v[40:43], v[134:137], v[146:149], v[40:43]
	s_waitcnt vmcnt(18)
	v_mfma_f32_16x16x32_bf16 v[44:47], v[138:141], v[146:149], v[44:47]
	s_waitcnt vmcnt(18)
	v_mfma_f32_16x16x32_bf16 v[48:51], v[142:145], v[146:149], v[48:51]
	global_load_dwordx4 v[146:149], v[98:99], off offset:128
	s_waitcnt vmcnt(18)
	v_mfma_f32_16x16x32_bf16 v[52:55], v[130:133], v[150:153], v[52:55]
	v_mfma_f32_16x16x32_bf16 v[32:35], v[134:137], v[150:153], v[32:35]
	v_mfma_f32_16x16x32_bf16 v[24:27], v[138:141], v[150:153], v[24:27]
	v_mfma_f32_16x16x32_bf16 v[12:15], v[142:145], v[150:153], v[12:15]
	global_load_dwordx4 v[150:153], v[112:113], off offset:144
	s_waitcnt vmcnt(18)
	v_mfma_f32_16x16x32_bf16 v[36:39], v[130:133], v[154:157], v[36:39]
	v_mfma_f32_16x16x32_bf16 v[28:31], v[134:137], v[154:157], v[28:31]
	v_mfma_f32_16x16x32_bf16 v[20:23], v[138:141], v[154:157], v[20:23]
	v_mfma_f32_16x16x32_bf16 v[8:11], v[142:145], v[154:157], v[8:11]
	global_load_dwordx4 v[154:157], v[110:111], off offset:144
	s_waitcnt vmcnt(18)
	v_mfma_f32_16x16x32_bf16 v[64:67], v[130:133], v[158:161], v[64:67]
	global_load_dwordx4 v[130:133], v[106:107], off offset:144
	v_mfma_f32_16x16x32_bf16 v[60:63], v[134:137], v[158:161], v[60:63]
	global_load_dwordx4 v[134:137], v[104:105], off offset:144
	v_mfma_f32_16x16x32_bf16 v[68:71], v[138:141], v[158:161], v[68:71]
	global_load_dwordx4 v[138:141], v[108:109], off offset:144
	v_mfma_f32_16x16x32_bf16 v[56:59], v[142:145], v[158:161], v[56:59]
	global_load_dwordx4 v[142:145], v[100:101], off offset:144
	global_load_dwordx4 v[158:161], v[102:103], off offset:144
	s_waitcnt vmcnt(18)
	v_mfma_f32_16x16x32_bf16 v[16:19], v[162:165], v[178:181], v[16:19]
	s_waitcnt vmcnt(18)
	v_mfma_f32_16x16x32_bf16 v[40:43], v[166:169], v[178:181], v[40:43]
	s_waitcnt vmcnt(18)
	v_mfma_f32_16x16x32_bf16 v[44:47], v[170:173], v[178:181], v[44:47]
	s_waitcnt vmcnt(18)
	v_mfma_f32_16x16x32_bf16 v[48:51], v[174:177], v[178:181], v[48:51]
	global_load_dwordx4 v[178:181], v[98:99], off offset:144
	s_waitcnt vmcnt(18)
	v_mfma_f32_16x16x32_bf16 v[52:55], v[162:165], v[182:185], v[52:55]
	v_mfma_f32_16x16x32_bf16 v[32:35], v[166:169], v[182:185], v[32:35]
	v_mfma_f32_16x16x32_bf16 v[24:27], v[170:173], v[182:185], v[24:27]
	v_mfma_f32_16x16x32_bf16 v[12:15], v[174:177], v[182:185], v[12:15]
	global_load_dwordx4 v[182:185], v[112:113], off offset:256
	s_waitcnt vmcnt(18)
	v_mfma_f32_16x16x32_bf16 v[36:39], v[162:165], v[186:189], v[36:39]
	v_mfma_f32_16x16x32_bf16 v[28:31], v[166:169], v[186:189], v[28:31]
	v_mfma_f32_16x16x32_bf16 v[20:23], v[170:173], v[186:189], v[20:23]
	v_mfma_f32_16x16x32_bf16 v[8:11], v[174:177], v[186:189], v[8:11]
	global_load_dwordx4 v[186:189], v[110:111], off offset:256
	s_waitcnt vmcnt(18)
	v_mfma_f32_16x16x32_bf16 v[64:67], v[162:165], v[198:201], v[64:67]
	global_load_dwordx4 v[162:165], v[106:107], off offset:256
	v_mfma_f32_16x16x32_bf16 v[60:63], v[166:169], v[198:201], v[60:63]
	global_load_dwordx4 v[166:169], v[104:105], off offset:256
	v_mfma_f32_16x16x32_bf16 v[68:71], v[170:173], v[198:201], v[68:71]
	global_load_dwordx4 v[170:173], v[108:109], off offset:256
	v_mfma_f32_16x16x32_bf16 v[56:59], v[174:177], v[198:201], v[56:59]
	global_load_dwordx4 v[174:177], v[100:101], off offset:256
	global_load_dwordx4 v[198:201], v[102:103], off offset:256
	s_waitcnt vmcnt(18)
	v_mfma_f32_16x16x32_bf16 v[16:19], v[218:221], v[234:237], v[16:19]
	s_waitcnt vmcnt(18)
	v_mfma_f32_16x16x32_bf16 v[40:43], v[222:225], v[234:237], v[40:43]
	s_waitcnt vmcnt(18)
	v_mfma_f32_16x16x32_bf16 v[44:47], v[226:229], v[234:237], v[44:47]
	s_waitcnt vmcnt(18)
	v_mfma_f32_16x16x32_bf16 v[48:51], v[230:233], v[234:237], v[48:51]
	global_load_dwordx4 v[234:237], v[98:99], off offset:256
	s_waitcnt vmcnt(18)
	v_mfma_f32_16x16x32_bf16 v[52:55], v[218:221], v[238:241], v[52:55]
	v_mfma_f32_16x16x32_bf16 v[32:35], v[222:225], v[238:241], v[32:35]
	v_mfma_f32_16x16x32_bf16 v[24:27], v[226:229], v[238:241], v[24:27]
	v_mfma_f32_16x16x32_bf16 v[12:15], v[230:233], v[238:241], v[12:15]
	global_load_dwordx4 v[238:241], v[112:113], off offset:272
	s_waitcnt vmcnt(18)
	v_mfma_f32_16x16x32_bf16 v[36:39], v[218:221], v[246:249], v[36:39]
	v_mfma_f32_16x16x32_bf16 v[28:31], v[222:225], v[246:249], v[28:31]
	v_mfma_f32_16x16x32_bf16 v[20:23], v[226:229], v[246:249], v[20:23]
	v_mfma_f32_16x16x32_bf16 v[8:11], v[230:233], v[246:249], v[8:11]
	global_load_dwordx4 v[246:249], v[110:111], off offset:272
	s_waitcnt vmcnt(18)
	v_mfma_f32_16x16x32_bf16 v[64:67], v[218:221], v[146:149], v[64:67]
	global_load_dwordx4 v[218:221], v[106:107], off offset:272
	v_mfma_f32_16x16x32_bf16 v[60:63], v[222:225], v[146:149], v[60:63]
	global_load_dwordx4 v[222:225], v[104:105], off offset:272
	v_mfma_f32_16x16x32_bf16 v[68:71], v[226:229], v[146:149], v[68:71]
	global_load_dwordx4 v[226:229], v[108:109], off offset:272
	v_mfma_f32_16x16x32_bf16 v[56:59], v[230:233], v[146:149], v[56:59]
	global_load_dwordx4 v[230:233], v[100:101], off offset:272
	global_load_dwordx4 v[146:149], v[102:103], off offset:272
	s_waitcnt vmcnt(18)
	v_mfma_f32_16x16x32_bf16 v[16:19], v[150:153], v[138:141], v[16:19]
	s_waitcnt vmcnt(18)
	v_mfma_f32_16x16x32_bf16 v[40:43], v[154:157], v[138:141], v[40:43]
	s_waitcnt vmcnt(18)
	v_mfma_f32_16x16x32_bf16 v[44:47], v[130:133], v[138:141], v[44:47]
	s_waitcnt vmcnt(18)
	v_mfma_f32_16x16x32_bf16 v[48:51], v[134:137], v[138:141], v[48:51]
	global_load_dwordx4 v[138:141], v[98:99], off offset:272
	s_waitcnt vmcnt(18)
	v_mfma_f32_16x16x32_bf16 v[52:55], v[150:153], v[142:145], v[52:55]
	v_mfma_f32_16x16x32_bf16 v[32:35], v[154:157], v[142:145], v[32:35]
	v_mfma_f32_16x16x32_bf16 v[24:27], v[130:133], v[142:145], v[24:27]
	v_mfma_f32_16x16x32_bf16 v[12:15], v[134:137], v[142:145], v[12:15]
	global_load_dwordx4 v[142:145], v[112:113], off offset:384
	s_waitcnt vmcnt(18)
	v_mfma_f32_16x16x32_bf16 v[36:39], v[150:153], v[158:161], v[36:39]
	v_mfma_f32_16x16x32_bf16 v[28:31], v[154:157], v[158:161], v[28:31]
	v_mfma_f32_16x16x32_bf16 v[20:23], v[130:133], v[158:161], v[20:23]
	v_mfma_f32_16x16x32_bf16 v[8:11], v[134:137], v[158:161], v[8:11]
	global_load_dwordx4 v[158:161], v[110:111], off offset:384
	s_waitcnt vmcnt(18)
	v_mfma_f32_16x16x32_bf16 v[64:67], v[150:153], v[178:181], v[64:67]
	global_load_dwordx4 v[150:153], v[106:107], off offset:384
	v_mfma_f32_16x16x32_bf16 v[60:63], v[154:157], v[178:181], v[60:63]
	global_load_dwordx4 v[154:157], v[104:105], off offset:384
	v_mfma_f32_16x16x32_bf16 v[68:71], v[130:133], v[178:181], v[68:71]
	global_load_dwordx4 v[130:133], v[108:109], off offset:384
	v_mfma_f32_16x16x32_bf16 v[56:59], v[134:137], v[178:181], v[56:59]
	global_load_dwordx4 v[134:137], v[100:101], off offset:384
	global_load_dwordx4 v[178:181], v[102:103], off offset:384
	s_waitcnt vmcnt(18)
	v_mfma_f32_16x16x32_bf16 v[16:19], v[182:185], v[170:173], v[16:19]
	s_waitcnt vmcnt(18)
	v_mfma_f32_16x16x32_bf16 v[40:43], v[186:189], v[170:173], v[40:43]
	s_waitcnt vmcnt(18)
	v_mfma_f32_16x16x32_bf16 v[44:47], v[162:165], v[170:173], v[44:47]
	s_waitcnt vmcnt(18)
	v_mfma_f32_16x16x32_bf16 v[48:51], v[166:169], v[170:173], v[48:51]
	global_load_dwordx4 v[170:173], v[98:99], off offset:384
	s_waitcnt vmcnt(18)
	v_mfma_f32_16x16x32_bf16 v[52:55], v[182:185], v[174:177], v[52:55]
	v_mfma_f32_16x16x32_bf16 v[32:35], v[186:189], v[174:177], v[32:35]
	v_mfma_f32_16x16x32_bf16 v[24:27], v[162:165], v[174:177], v[24:27]
	v_mfma_f32_16x16x32_bf16 v[12:15], v[166:169], v[174:177], v[12:15]
	global_load_dwordx4 v[174:177], v[112:113], off offset:400
	s_waitcnt vmcnt(18)
	v_mfma_f32_16x16x32_bf16 v[36:39], v[182:185], v[198:201], v[36:39]
	v_mfma_f32_16x16x32_bf16 v[28:31], v[186:189], v[198:201], v[28:31]
	v_mfma_f32_16x16x32_bf16 v[20:23], v[162:165], v[198:201], v[20:23]
	v_mfma_f32_16x16x32_bf16 v[8:11], v[166:169], v[198:201], v[8:11]
	global_load_dwordx4 v[198:201], v[110:111], off offset:400
	s_waitcnt vmcnt(18)
	v_mfma_f32_16x16x32_bf16 v[64:67], v[182:185], v[234:237], v[64:67]
	global_load_dwordx4 v[182:185], v[106:107], off offset:400
	v_mfma_f32_16x16x32_bf16 v[60:63], v[186:189], v[234:237], v[60:63]
	global_load_dwordx4 v[186:189], v[104:105], off offset:400
	v_mfma_f32_16x16x32_bf16 v[68:71], v[162:165], v[234:237], v[68:71]
	global_load_dwordx4 v[162:165], v[108:109], off offset:400
	v_mfma_f32_16x16x32_bf16 v[56:59], v[166:169], v[234:237], v[56:59]
	global_load_dwordx4 v[166:169], v[100:101], off offset:400
	global_load_dwordx4 v[234:237], v[102:103], off offset:400
	s_waitcnt vmcnt(18)
	v_mfma_f32_16x16x32_bf16 v[16:19], v[238:241], v[226:229], v[16:19]
	s_waitcnt vmcnt(18)
	v_mfma_f32_16x16x32_bf16 v[40:43], v[246:249], v[226:229], v[40:43]
	s_waitcnt vmcnt(18)
	v_mfma_f32_16x16x32_bf16 v[44:47], v[218:221], v[226:229], v[44:47]
	s_waitcnt vmcnt(18)
	v_mfma_f32_16x16x32_bf16 v[48:51], v[222:225], v[226:229], v[48:51]
	global_load_dwordx4 v[226:229], v[98:99], off offset:400
	s_waitcnt vmcnt(18)
	v_mfma_f32_16x16x32_bf16 v[52:55], v[238:241], v[230:233], v[52:55]
	v_mfma_f32_16x16x32_bf16 v[32:35], v[246:249], v[230:233], v[32:35]
	v_mfma_f32_16x16x32_bf16 v[24:27], v[218:221], v[230:233], v[24:27]
	v_mfma_f32_16x16x32_bf16 v[12:15], v[222:225], v[230:233], v[12:15]
	s_waitcnt vmcnt(17)
	v_mfma_f32_16x16x32_bf16 v[36:39], v[238:241], v[146:149], v[36:39]
	v_mfma_f32_16x16x32_bf16 v[28:31], v[246:249], v[146:149], v[28:31]
	v_mfma_f32_16x16x32_bf16 v[20:23], v[218:221], v[146:149], v[20:23]
	v_mfma_f32_16x16x32_bf16 v[8:11], v[222:225], v[146:149], v[8:11]
	s_waitcnt vmcnt(16)
	v_mfma_f32_16x16x32_bf16 v[64:67], v[238:241], v[138:141], v[64:67]
	v_mfma_f32_16x16x32_bf16 v[60:63], v[246:249], v[138:141], v[60:63]
	v_mfma_f32_16x16x32_bf16 v[68:71], v[218:221], v[138:141], v[68:71]
	v_mfma_f32_16x16x32_bf16 v[56:59], v[222:225], v[138:141], v[56:59]
	s_waitcnt vmcnt(11)
	v_mfma_f32_16x16x32_bf16 v[16:19], v[142:145], v[130:133], v[16:19]
	s_waitcnt vmcnt(11)
	v_mfma_f32_16x16x32_bf16 v[40:43], v[158:161], v[130:133], v[40:43]
	s_waitcnt vmcnt(11)
	v_mfma_f32_16x16x32_bf16 v[44:47], v[150:153], v[130:133], v[44:47]
	s_waitcnt vmcnt(11)
	v_mfma_f32_16x16x32_bf16 v[48:51], v[154:157], v[130:133], v[48:51]
	s_waitcnt vmcnt(10)
	v_mfma_f32_16x16x32_bf16 v[52:55], v[142:145], v[134:137], v[52:55]
	v_mfma_f32_16x16x32_bf16 v[32:35], v[158:161], v[134:137], v[32:35]
	v_mfma_f32_16x16x32_bf16 v[24:27], v[150:153], v[134:137], v[24:27]
	v_mfma_f32_16x16x32_bf16 v[12:15], v[154:157], v[134:137], v[12:15]
	s_waitcnt vmcnt(9)
	v_mfma_f32_16x16x32_bf16 v[36:39], v[142:145], v[178:181], v[36:39]
	v_mfma_f32_16x16x32_bf16 v[28:31], v[158:161], v[178:181], v[28:31]
	v_mfma_f32_16x16x32_bf16 v[20:23], v[150:153], v[178:181], v[20:23]
	v_mfma_f32_16x16x32_bf16 v[8:11], v[154:157], v[178:181], v[8:11]
	s_waitcnt vmcnt(8)
	v_mfma_f32_16x16x32_bf16 v[64:67], v[142:145], v[170:173], v[64:67]
	v_mfma_f32_16x16x32_bf16 v[60:63], v[158:161], v[170:173], v[60:63]
	v_mfma_f32_16x16x32_bf16 v[68:71], v[150:153], v[170:173], v[68:71]
	v_mfma_f32_16x16x32_bf16 v[56:59], v[154:157], v[170:173], v[56:59]
	s_waitcnt vmcnt(3)
	v_mfma_f32_16x16x32_bf16 v[16:19], v[174:177], v[162:165], v[16:19]
	s_waitcnt vmcnt(3)
	v_mfma_f32_16x16x32_bf16 v[40:43], v[198:201], v[162:165], v[40:43]
	s_waitcnt vmcnt(3)
	v_mfma_f32_16x16x32_bf16 v[44:47], v[182:185], v[162:165], v[44:47]
	s_waitcnt vmcnt(3)
	v_mfma_f32_16x16x32_bf16 v[48:51], v[186:189], v[162:165], v[48:51]
	s_waitcnt vmcnt(2)
	v_mfma_f32_16x16x32_bf16 v[52:55], v[174:177], v[166:169], v[52:55]
	v_mfma_f32_16x16x32_bf16 v[32:35], v[198:201], v[166:169], v[32:35]
	v_mfma_f32_16x16x32_bf16 v[24:27], v[182:185], v[166:169], v[24:27]
	v_mfma_f32_16x16x32_bf16 v[12:15], v[186:189], v[166:169], v[12:15]
	s_waitcnt vmcnt(1)
	v_mfma_f32_16x16x32_bf16 v[36:39], v[174:177], v[234:237], v[36:39]
	v_mfma_f32_16x16x32_bf16 v[28:31], v[198:201], v[234:237], v[28:31]
	v_mfma_f32_16x16x32_bf16 v[20:23], v[182:185], v[234:237], v[20:23]
	v_mfma_f32_16x16x32_bf16 v[8:11], v[186:189], v[234:237], v[8:11]
	s_waitcnt vmcnt(0)
	v_mfma_f32_16x16x32_bf16 v[64:67], v[174:177], v[226:229], v[64:67]
	v_mfma_f32_16x16x32_bf16 v[60:63], v[198:201], v[226:229], v[60:63]
	v_mfma_f32_16x16x32_bf16 v[68:71], v[182:185], v[226:229], v[68:71]
	v_mfma_f32_16x16x32_bf16 v[56:59], v[186:189], v[226:229], v[56:59]
	s_branch .LBB0_607
